# prompt fast tile path: cross-half max via permlane32_swap instead of ds_bpermute, PV kk0+kk1 MFMAs issued before the second-half softmax
# speedup vs baseline: 1.0206x; 1.0088x over previous
; __device__ __forceinline__ float fexp2(float x) { return __builtin_amdgcn_exp2f(x); }
; template <int NEB>
; __device__ __forceinline__ void softmax_tile(f32x16& X0, f32x16& X1, float& m, float& l, f32x16 (&OT)[NEB]) {
;     float mx = X0[0];
; #pragma unroll
;     for (int r = 1; r < 16; ++r) mx = fmaxf(mx, X0[r]);
; #pragma unroll
;     for (int r = 0; r < 16; ++r) mx = fmaxf(mx, X1[r]);
;     mx = fmaxf(mx, __shfl_xor(mx, 32));
;     if (__any(mx > m + 8.f)) {
;         const float mn = fmaxf(m, mx), alpha = fexp2(m - mn); m = mn; l *= alpha;
; #pragma unroll
;         for (int e = 0; e < NEB; ++e) OT[e] = OT[e] * alpha;
;     }
.Lp_e1_skip:
	s_cmp_ge_u32 s15, s14
	s_cbranch_scc1 .LBB0_931
	s_add_i32 s99, s15, 1
	s_cmp_ge_u32 s99, s14
	s_cbranch_scc1 .Lpf0_slow
	ds_read_b128 v[66:69], v162
	ds_read_b128 v[166:169], v162 offset:32
	ds_read_b128 v[82:85], v162 offset:4608
	ds_read_b128 v[176:179], v162 offset:4640
	v_cvt_f32_i32_e32 v186, v158
	s_waitcnt lgkmcnt(3)
	v_mfma_f32_32x32x16_bf16 v[66:81], v[66:69], v[110:113], v[210:225]
	v_mul_f32_e64 v175, -v153, v186
	s_waitcnt lgkmcnt(1)
	v_mfma_f32_32x32x16_bf16 v[82:97], v[82:85], v[110:113], v[226:241]
	v_mfma_f32_32x32x16_bf16 v[66:81], v[166:169], v[106:109], v[66:81]
	s_waitcnt lgkmcnt(0)
	v_mfma_f32_32x32x16_bf16 v[82:97], v[176:179], v[106:109], v[82:97]
	ds_read_b128 v[166:169], v162 offset:64
	ds_read_b128 v[176:179], v162 offset:96
	s_waitcnt lgkmcnt(1)
	v_mfma_f32_32x32x16_bf16 v[66:81], v[166:169], v[102:105], v[66:81]
	ds_read_b128 v[166:169], v162 offset:4672
	ds_read_b128 v[182:185], v162 offset:4704
	s_waitcnt lgkmcnt(1)
	v_mfma_f32_32x32x16_bf16 v[82:97], v[166:169], v[102:105], v[82:97]
	v_mfma_f32_32x32x16_bf16 v[66:81], v[176:179], v[98:101], v[66:81]
	s_waitcnt lgkmcnt(0)
	v_mfma_f32_32x32x16_bf16 v[82:97], v[182:185], v[98:101], v[82:97]
	ds_read_b64_tr_b16 v[166:167], v156 offset:18432
	ds_read_b64_tr_b16 v[168:169], v156 offset:20992
	ds_read_b64_tr_b16 v[176:177], v156 offset:18496
	ds_read_b64_tr_b16 v[178:179], v156 offset:21056
	ds_read_b64_tr_b16 v[180:181], v156 offset:18560
	ds_read_b64_tr_b16 v[182:183], v156 offset:21120
	ds_read_b64_tr_b16 v[184:185], v156 offset:18624
	ds_read_b64_tr_b16 v[186:187], v156 offset:21184
	s_nop 5
	v_max3_f32 v0, v66, v67, v68
	v_max3_f32 v151, v82, v83, v84
	v_max3_f32 v0, v0, v69, v70
	v_max3_f32 v151, v151, v85, v86
	v_max3_f32 v0, v0, v71, v72
	v_max3_f32 v151, v151, v87, v88
	v_max3_f32 v0, v0, v73, v74
	v_max3_f32 v151, v151, v89, v90
	v_max3_f32 v0, v0, v75, v76
	v_max3_f32 v151, v151, v91, v92
	v_max3_f32 v0, v0, v77, v78
	v_max3_f32 v151, v151, v93, v94
	v_max3_f32 v0, v0, v79, v80
	v_max3_f32 v151, v151, v95, v96
	v_max3_f32 v0, v0, v81, v151
	v_max_f32_e32 v0, v0, v97
	v_add_f32_e32 v0, v0, v175
	v_mov_b32_e32 v164, v0
	s_nop 1
	v_permlane32_swap_b32_e32 v164, v0
	s_nop 0
	v_max_f32_e32 v0, v0, v164
	v_add_f32_e32 v164, 0x41000000, v163
	v_cmp_gt_f32_e32 vcc, v0, v164
	s_cbranch_vccz .Lpf0_nores
	v_max_f32_e32 v0, v163, v0
	v_sub_f32_e32 v164, v163, v0
	v_exp_f32_e32 v164, v164
	v_mov_b32_e32 v163, v0
	s_nop 0
	v_mul_f32_e32 v159, v159, v164
	v_pk_mul_f32 v[64:65], v[64:65], v[164:165] op_sel_hi:[1,0]
	v_pk_mul_f32 v[62:63], v[62:63], v[164:165] op_sel_hi:[1,0]
	v_pk_mul_f32 v[60:61], v[60:61], v[164:165] op_sel_hi:[1,0]
	v_pk_mul_f32 v[58:59], v[58:59], v[164:165] op_sel_hi:[1,0]
	v_pk_mul_f32 v[56:57], v[56:57], v[164:165] op_sel_hi:[1,0]
	v_pk_mul_f32 v[54:55], v[54:55], v[164:165] op_sel_hi:[1,0]
	v_pk_mul_f32 v[52:53], v[52:53], v[164:165] op_sel_hi:[1,0]
	v_pk_mul_f32 v[50:51], v[50:51], v[164:165] op_sel_hi:[1,0]
	v_pk_mul_f32 v[48:49], v[48:49], v[164:165] op_sel_hi:[1,0]
	v_pk_mul_f32 v[46:47], v[46:47], v[164:165] op_sel_hi:[1,0]
	v_pk_mul_f32 v[44:45], v[44:45], v[164:165] op_sel_hi:[1,0]
	v_pk_mul_f32 v[42:43], v[42:43], v[164:165] op_sel_hi:[1,0]
	v_pk_mul_f32 v[40:41], v[40:41], v[164:165] op_sel_hi:[1,0]
	v_pk_mul_f32 v[38:39], v[38:39], v[164:165] op_sel_hi:[1,0]
	v_pk_mul_f32 v[36:37], v[36:37], v[164:165] op_sel_hi:[1,0]
	v_pk_mul_f32 v[34:35], v[34:35], v[164:165] op_sel_hi:[1,0]
	v_pk_mul_f32 v[32:33], v[32:33], v[164:165] op_sel_hi:[1,0]
	v_pk_mul_f32 v[30:31], v[30:31], v[164:165] op_sel_hi:[1,0]
	v_pk_mul_f32 v[28:29], v[28:29], v[164:165] op_sel_hi:[1,0]
	v_pk_mul_f32 v[26:27], v[26:27], v[164:165] op_sel_hi:[1,0]
	v_pk_mul_f32 v[24:25], v[24:25], v[164:165] op_sel_hi:[1,0]
	v_pk_mul_f32 v[22:23], v[22:23], v[164:165] op_sel_hi:[1,0]
	v_pk_mul_f32 v[20:21], v[20:21], v[164:165] op_sel_hi:[1,0]
	v_pk_mul_f32 v[18:19], v[18:19], v[164:165] op_sel_hi:[1,0]
	v_pk_mul_f32 v[16:17], v[16:17], v[164:165] op_sel_hi:[1,0]
	v_pk_mul_f32 v[14:15], v[14:15], v[164:165] op_sel_hi:[1,0]
	v_pk_mul_f32 v[12:13], v[12:13], v[164:165] op_sel_hi:[1,0]
	v_pk_mul_f32 v[10:11], v[10:11], v[164:165] op_sel_hi:[1,0]
	v_pk_mul_f32 v[8:9], v[8:9], v[164:165] op_sel_hi:[1,0]
	v_pk_mul_f32 v[6:7], v[6:7], v[164:165] op_sel_hi:[1,0]
	v_pk_mul_f32 v[4:5], v[4:5], v[164:165] op_sel_hi:[1,0]
	v_pk_mul_f32 v[2:3], v[2:3], v[164:165] op_sel_hi:[1,0]
; #define LAS __attribute__((address_space(3)))
; __device__ __forceinline__ float fexp2(float x) { return __builtin_amdgcn_exp2f(x); }
; __device__ __forceinline__ s16x4 vtr(const LAS unsigned char* p) { return __builtin_bit_cast(s16x4, __builtin_amdgcn_ds_read_tr16_b64_v4i16((LAS v4i16_t*)p)); }
; __device__ __forceinline__ bf16x8 cat8(s16x4 lo, s16x4 hi) { return (bf16x8){lo[0], lo[1], lo[2], lo[3], hi[0], hi[1], hi[2], hi[3]}; }
; template <int NEB>
; __device__ __forceinline__ void softmax_tile(f32x16& X0, f32x16& X1, float& m, float& l, f32x16 (&OT)[NEB]) {
;     ...
;     float s = 0.f;
; #pragma unroll
;     for (int r = 0; r < 16; ++r) { X0[r] = fexp2(X0[r] - m); X1[r] = fexp2(X1[r] - m); s += X0[r] + X1[r]; }
;     l += s;
; }
; template <int VRS, int NEB, bool SB = false>
; __device__ __forceinline__ void pv_tile(f32x16 (&OT)[NEB], const f32x16& X0, const f32x16& X1, const LAS unsigned char* vlane  ) {
; #pragma unroll
;     for (int kk = 0; kk < 4; ++kk) {
;         const bf16x8 pa = packp(kk < 2 ? X0 : X1, (kk & 1) * 8);
; #pragma unroll
;         for (int eb = 0; eb < NEB; ++eb) {
;             const s16x4 lo = vtr(vlane + (kk * 16) * VRS + eb * 64), hi = vtr(vlane + (kk * 16 + 8) * VRS + eb * 64);
;             OT[eb] = __builtin_amdgcn_mfma_f32_32x32x16_bf16(cat8(lo, hi), pa, OT[eb], 0, 0, 0);
;         }
;         if (SB) __builtin_amdgcn_sched_barrier(0);
;     }
; }
.Lpf0_nores:
	v_sub_f32_e32 v164, v175, v163
	v_pk_add_f32 v[66:67], v[66:67], v[164:165] op_sel_hi:[1,0]
	v_pk_add_f32 v[68:69], v[68:69], v[164:165] op_sel_hi:[1,0]
	v_pk_add_f32 v[70:71], v[70:71], v[164:165] op_sel_hi:[1,0]
	v_pk_add_f32 v[72:73], v[72:73], v[164:165] op_sel_hi:[1,0]
	v_pk_add_f32 v[74:75], v[74:75], v[164:165] op_sel_hi:[1,0]
	v_pk_add_f32 v[76:77], v[76:77], v[164:165] op_sel_hi:[1,0]
	v_pk_add_f32 v[78:79], v[78:79], v[164:165] op_sel_hi:[1,0]
	v_pk_add_f32 v[80:81], v[80:81], v[164:165] op_sel_hi:[1,0]
	v_exp_f32_e32 v66, v66
	v_exp_f32_e32 v67, v67
	v_exp_f32_e32 v68, v68
	v_exp_f32_e32 v69, v69
	v_exp_f32_e32 v70, v70
	v_exp_f32_e32 v71, v71
	v_exp_f32_e32 v72, v72
	v_exp_f32_e32 v73, v73
	v_exp_f32_e32 v74, v74
	v_exp_f32_e32 v75, v75
	v_exp_f32_e32 v76, v76
	v_exp_f32_e32 v77, v77
	v_exp_f32_e32 v78, v78
	v_exp_f32_e32 v79, v79
	v_exp_f32_e32 v80, v80
	v_exp_f32_e32 v81, v81
	v_pk_add_f32 v[188:189], v[66:67], v[68:69]
	v_pk_add_f32 v[190:191], v[70:71], v[72:73]
	v_pk_add_f32 v[188:189], v[188:189], v[74:75]
	v_pk_add_f32 v[190:191], v[190:191], v[76:77]
	v_pk_add_f32 v[188:189], v[188:189], v[78:79]
	v_pk_add_f32 v[190:191], v[190:191], v[80:81]
	v_cvt_pk_bf16_f32 v66, v66, v67
	v_cvt_pk_bf16_f32 v67, v68, v69
	v_cvt_pk_bf16_f32 v68, v70, v71
	v_cvt_pk_bf16_f32 v69, v72, v73
	v_cvt_pk_bf16_f32 v70, v74, v75
	v_cvt_pk_bf16_f32 v71, v76, v77
	v_cvt_pk_bf16_f32 v72, v78, v79
	v_cvt_pk_bf16_f32 v73, v80, v81
	ds_read_b64_tr_b16 v[74:75], v156 offset:23552
	ds_read_b64_tr_b16 v[76:77], v156 offset:26112
	ds_read_b64_tr_b16 v[78:79], v156 offset:23616
	ds_read_b64_tr_b16 v[80:81], v156 offset:26176
	ds_read_b64_tr_b16 v[244:245], v156 offset:23680
	ds_read_b64_tr_b16 v[246:247], v156 offset:26240
	ds_read_b64_tr_b16 v[248:249], v156 offset:23744
	ds_read_b64_tr_b16 v[250:251], v156 offset:26304
	s_waitcnt lgkmcnt(8)
	v_mfma_f32_32x32x16_bf16 v[50:65], v[166:169], v[66:69], v[50:65]
	v_mfma_f32_32x32x16_bf16 v[34:49], v[176:179], v[66:69], v[34:49]
	v_mfma_f32_32x32x16_bf16 v[18:33], v[180:183], v[66:69], v[18:33]
	v_mfma_f32_32x32x16_bf16 v[2:17], v[184:187], v[66:69], v[2:17]
	ds_read_b64_tr_b16 v[166:167], v156 offset:28672
	ds_read_b64_tr_b16 v[168:169], v156 offset:31232
	ds_read_b64_tr_b16 v[176:177], v156 offset:28736
	ds_read_b64_tr_b16 v[178:179], v156 offset:31296
	ds_read_b64_tr_b16 v[180:181], v156 offset:28800
	ds_read_b64_tr_b16 v[182:183], v156 offset:31360
	ds_read_b64_tr_b16 v[184:185], v156 offset:28864
	ds_read_b64_tr_b16 v[186:187], v156 offset:31424
	s_waitcnt lgkmcnt(8)
	v_mfma_f32_32x32x16_bf16 v[50:65], v[74:77], v[70:73], v[50:65]
	v_mfma_f32_32x32x16_bf16 v[34:49], v[78:81], v[70:73], v[34:49]
	v_mfma_f32_32x32x16_bf16 v[18:33], v[244:247], v[70:73], v[18:33]
	v_mfma_f32_32x32x16_bf16 v[2:17], v[248:251], v[70:73], v[2:17]
	ds_read_b64_tr_b16 v[74:75], v156 offset:33792
	ds_read_b64_tr_b16 v[76:77], v156 offset:36352
	ds_read_b64_tr_b16 v[78:79], v156 offset:33856
	ds_read_b64_tr_b16 v[80:81], v156 offset:36416
	ds_read_b64_tr_b16 v[244:245], v156 offset:33920
	ds_read_b64_tr_b16 v[246:247], v156 offset:36480
	ds_read_b64_tr_b16 v[248:249], v156 offset:33984
	ds_read_b64_tr_b16 v[250:251], v156 offset:36544
	v_pk_add_f32 v[82:83], v[82:83], v[164:165] op_sel_hi:[1,0]
	v_pk_add_f32 v[84:85], v[84:85], v[164:165] op_sel_hi:[1,0]
	v_pk_add_f32 v[86:87], v[86:87], v[164:165] op_sel_hi:[1,0]
	v_pk_add_f32 v[88:89], v[88:89], v[164:165] op_sel_hi:[1,0]
	v_pk_add_f32 v[90:91], v[90:91], v[164:165] op_sel_hi:[1,0]
	v_pk_add_f32 v[92:93], v[92:93], v[164:165] op_sel_hi:[1,0]
	v_pk_add_f32 v[94:95], v[94:95], v[164:165] op_sel_hi:[1,0]
	v_pk_add_f32 v[96:97], v[96:97], v[164:165] op_sel_hi:[1,0]
	v_exp_f32_e32 v82, v82
	v_exp_f32_e32 v83, v83
	v_exp_f32_e32 v84, v84
	v_exp_f32_e32 v85, v85
	v_exp_f32_e32 v86, v86
	v_exp_f32_e32 v87, v87
	v_exp_f32_e32 v88, v88
	v_exp_f32_e32 v89, v89
	v_exp_f32_e32 v90, v90
	v_exp_f32_e32 v91, v91
	v_exp_f32_e32 v92, v92
	v_exp_f32_e32 v93, v93
	v_exp_f32_e32 v94, v94
	v_exp_f32_e32 v95, v95
	v_exp_f32_e32 v96, v96
	v_exp_f32_e32 v97, v97
	v_pk_add_f32 v[188:189], v[188:189], v[82:83]
	v_pk_add_f32 v[190:191], v[190:191], v[84:85]
	v_pk_add_f32 v[188:189], v[188:189], v[86:87]
	v_pk_add_f32 v[190:191], v[190:191], v[88:89]
	v_pk_add_f32 v[188:189], v[188:189], v[90:91]
	v_pk_add_f32 v[190:191], v[190:191], v[92:93]
	v_pk_add_f32 v[188:189], v[188:189], v[94:95]
	v_pk_add_f32 v[190:191], v[190:191], v[96:97]
	v_cvt_pk_bf16_f32 v82, v82, v83
	v_cvt_pk_bf16_f32 v83, v84, v85
	v_cvt_pk_bf16_f32 v84, v86, v87
	v_cvt_pk_bf16_f32 v85, v88, v89
	v_cvt_pk_bf16_f32 v86, v90, v91
	v_cvt_pk_bf16_f32 v87, v92, v93
	v_cvt_pk_bf16_f32 v88, v94, v95
	v_cvt_pk_bf16_f32 v89, v96, v97
	v_pk_add_f32 v[188:189], v[188:189], v[190:191]
	s_waitcnt lgkmcnt(8)
	v_mfma_f32_32x32x16_bf16 v[50:65], v[166:169], v[82:85], v[50:65]
	v_mfma_f32_32x32x16_bf16 v[34:49], v[176:179], v[82:85], v[34:49]
	v_mfma_f32_32x32x16_bf16 v[18:33], v[180:183], v[82:85], v[18:33]
	v_mfma_f32_32x32x16_bf16 v[2:17], v[184:187], v[82:85], v[2:17]
	v_add_f32_e32 v0, v188, v189
	v_add_f32_e32 v159, v159, v0
	s_waitcnt lgkmcnt(0)
	v_mfma_f32_32x32x16_bf16 v[50:65], v[74:77], v[86:89], v[50:65]
	v_mfma_f32_32x32x16_bf16 v[34:49], v[78:81], v[86:89], v[34:49]
	v_mfma_f32_32x32x16_bf16 v[18:33], v[244:247], v[86:89], v[18:33]
	v_mfma_f32_32x32x16_bf16 v[2:17], v[248:251], v[86:89], v[2:17]
	s_branch .LBB0_931

; __device__ __forceinline__ float fexp2(float x) { return __builtin_amdgcn_exp2f(x); }
; template <int NEB>
; __device__ __forceinline__ void softmax_tile(f32x16& X0, f32x16& X1, float& m, float& l, f32x16 (&OT)[NEB]) {
;     float mx = X0[0];
; #pragma unroll
;     for (int r = 1; r < 16; ++r) mx = fmaxf(mx, X0[r]);
; #pragma unroll
;     for (int r = 0; r < 16; ++r) mx = fmaxf(mx, X1[r]);
;     mx = fmaxf(mx, __shfl_xor(mx, 32));
;     if (__any(mx > m + 8.f)) {
;         const float mn = fmaxf(m, mx), alpha = fexp2(m - mn); m = mn; l *= alpha;
; #pragma unroll
;         for (int e = 0; e < NEB; ++e) OT[e] = OT[e] * alpha;
;     }
.LBB0_935:
	s_add_i32 s99, s28, 1
	s_cmp_ge_u32 s99, s14
	s_cbranch_scc1 .Lpf1_slow
	ds_read_b128 v[66:69], v162 offset:38912
	ds_read_b128 v[166:169], v162 offset:38944
	ds_read_b128 v[82:85], v162 offset:43520
	ds_read_b128 v[176:179], v162 offset:43552
	v_subrev_u32_e32 v0, 64, v158
	v_cvt_f32_i32_e32 v186, v0
	s_waitcnt lgkmcnt(3)
	v_mfma_f32_32x32x16_bf16 v[66:81], v[66:69], v[110:113], v[210:225]
	v_mul_f32_e64 v175, -v153, v186
	s_waitcnt lgkmcnt(1)
	v_mfma_f32_32x32x16_bf16 v[82:97], v[82:85], v[110:113], v[226:241]
	v_mfma_f32_32x32x16_bf16 v[66:81], v[166:169], v[106:109], v[66:81]
	s_waitcnt lgkmcnt(0)
	v_mfma_f32_32x32x16_bf16 v[82:97], v[176:179], v[106:109], v[82:97]
	ds_read_b128 v[166:169], v162 offset:38976
	ds_read_b128 v[176:179], v162 offset:39008
	s_waitcnt lgkmcnt(1)
	v_mfma_f32_32x32x16_bf16 v[66:81], v[166:169], v[102:105], v[66:81]
	ds_read_b128 v[166:169], v162 offset:43584
	ds_read_b128 v[182:185], v162 offset:43616
	s_waitcnt lgkmcnt(1)
	v_mfma_f32_32x32x16_bf16 v[82:97], v[166:169], v[102:105], v[82:97]
	v_mfma_f32_32x32x16_bf16 v[66:81], v[176:179], v[98:101], v[66:81]
	s_waitcnt lgkmcnt(0)
	v_mfma_f32_32x32x16_bf16 v[82:97], v[182:185], v[98:101], v[82:97]
	ds_read_b64_tr_b16 v[166:167], v156 offset:57344
	ds_read_b64_tr_b16 v[168:169], v156 offset:59904
	ds_read_b64_tr_b16 v[176:177], v156 offset:57408
	ds_read_b64_tr_b16 v[178:179], v156 offset:59968
	ds_read_b64_tr_b16 v[180:181], v156 offset:57472
	ds_read_b64_tr_b16 v[182:183], v156 offset:60032
	ds_read_b64_tr_b16 v[184:185], v156 offset:57536
	ds_read_b64_tr_b16 v[186:187], v156 offset:60096
	s_nop 5
	v_max3_f32 v0, v66, v67, v68
	v_max3_f32 v151, v82, v83, v84
	v_max3_f32 v0, v0, v69, v70
	v_max3_f32 v151, v151, v85, v86
	v_max3_f32 v0, v0, v71, v72
	v_max3_f32 v151, v151, v87, v88
	v_max3_f32 v0, v0, v73, v74
	v_max3_f32 v151, v151, v89, v90
	v_max3_f32 v0, v0, v75, v76
	v_max3_f32 v151, v151, v91, v92
	v_max3_f32 v0, v0, v77, v78
	v_max3_f32 v151, v151, v93, v94
	v_max3_f32 v0, v0, v79, v80
	v_max3_f32 v151, v151, v95, v96
	v_max3_f32 v0, v0, v81, v151
	v_max_f32_e32 v0, v0, v97
	v_add_f32_e32 v0, v0, v175
	v_mov_b32_e32 v164, v0
	s_nop 1
	v_permlane32_swap_b32_e32 v164, v0
	s_nop 0
	v_max_f32_e32 v0, v0, v164
	v_add_f32_e32 v164, 0x41000000, v163
	v_cmp_gt_f32_e32 vcc, v0, v164
	s_cbranch_vccz .Lpf1_nores
	v_max_f32_e32 v0, v163, v0
	v_sub_f32_e32 v164, v163, v0
	v_exp_f32_e32 v164, v164
	v_mov_b32_e32 v163, v0
	s_nop 0
	v_mul_f32_e32 v159, v159, v164
	v_pk_mul_f32 v[64:65], v[64:65], v[164:165] op_sel_hi:[1,0]
	v_pk_mul_f32 v[62:63], v[62:63], v[164:165] op_sel_hi:[1,0]
	v_pk_mul_f32 v[60:61], v[60:61], v[164:165] op_sel_hi:[1,0]
	v_pk_mul_f32 v[58:59], v[58:59], v[164:165] op_sel_hi:[1,0]
	v_pk_mul_f32 v[56:57], v[56:57], v[164:165] op_sel_hi:[1,0]
	v_pk_mul_f32 v[54:55], v[54:55], v[164:165] op_sel_hi:[1,0]
	v_pk_mul_f32 v[52:53], v[52:53], v[164:165] op_sel_hi:[1,0]
	v_pk_mul_f32 v[50:51], v[50:51], v[164:165] op_sel_hi:[1,0]
	v_pk_mul_f32 v[48:49], v[48:49], v[164:165] op_sel_hi:[1,0]
	v_pk_mul_f32 v[46:47], v[46:47], v[164:165] op_sel_hi:[1,0]
	v_pk_mul_f32 v[44:45], v[44:45], v[164:165] op_sel_hi:[1,0]
	v_pk_mul_f32 v[42:43], v[42:43], v[164:165] op_sel_hi:[1,0]
	v_pk_mul_f32 v[40:41], v[40:41], v[164:165] op_sel_hi:[1,0]
	v_pk_mul_f32 v[38:39], v[38:39], v[164:165] op_sel_hi:[1,0]
	v_pk_mul_f32 v[36:37], v[36:37], v[164:165] op_sel_hi:[1,0]
	v_pk_mul_f32 v[34:35], v[34:35], v[164:165] op_sel_hi:[1,0]
	v_pk_mul_f32 v[32:33], v[32:33], v[164:165] op_sel_hi:[1,0]
	v_pk_mul_f32 v[30:31], v[30:31], v[164:165] op_sel_hi:[1,0]
	v_pk_mul_f32 v[28:29], v[28:29], v[164:165] op_sel_hi:[1,0]
	v_pk_mul_f32 v[26:27], v[26:27], v[164:165] op_sel_hi:[1,0]
	v_pk_mul_f32 v[24:25], v[24:25], v[164:165] op_sel_hi:[1,0]
	v_pk_mul_f32 v[22:23], v[22:23], v[164:165] op_sel_hi:[1,0]
	v_pk_mul_f32 v[20:21], v[20:21], v[164:165] op_sel_hi:[1,0]
	v_pk_mul_f32 v[18:19], v[18:19], v[164:165] op_sel_hi:[1,0]
	v_pk_mul_f32 v[16:17], v[16:17], v[164:165] op_sel_hi:[1,0]
	v_pk_mul_f32 v[14:15], v[14:15], v[164:165] op_sel_hi:[1,0]
	v_pk_mul_f32 v[12:13], v[12:13], v[164:165] op_sel_hi:[1,0]
	v_pk_mul_f32 v[10:11], v[10:11], v[164:165] op_sel_hi:[1,0]
	v_pk_mul_f32 v[8:9], v[8:9], v[164:165] op_sel_hi:[1,0]
	v_pk_mul_f32 v[6:7], v[6:7], v[164:165] op_sel_hi:[1,0]
	v_pk_mul_f32 v[4:5], v[4:5], v[164:165] op_sel_hi:[1,0]
	v_pk_mul_f32 v[2:3], v[2:3], v[164:165] op_sel_hi:[1,0]
; #define LAS __attribute__((address_space(3)))
; __device__ __forceinline__ float fexp2(float x) { return __builtin_amdgcn_exp2f(x); }
; __device__ __forceinline__ s16x4 vtr(const LAS unsigned char* p) { return __builtin_bit_cast(s16x4, __builtin_amdgcn_ds_read_tr16_b64_v4i16((LAS v4i16_t*)p)); }
; __device__ __forceinline__ bf16x8 cat8(s16x4 lo, s16x4 hi) { return (bf16x8){lo[0], lo[1], lo[2], lo[3], hi[0], hi[1], hi[2], hi[3]}; }
; template <int NEB>
; __device__ __forceinline__ void softmax_tile(f32x16& X0, f32x16& X1, float& m, float& l, f32x16 (&OT)[NEB]) {
;     ...
;     float s = 0.f;
; #pragma unroll
;     for (int r = 0; r < 16; ++r) { X0[r] = fexp2(X0[r] - m); X1[r] = fexp2(X1[r] - m); s += X0[r] + X1[r]; }
;     l += s;
; }
; template <int VRS, int NEB, bool SB = false>
; __device__ __forceinline__ void pv_tile(f32x16 (&OT)[NEB], const f32x16& X0, const f32x16& X1, const LAS unsigned char* vlane  ) {
; #pragma unroll
;     for (int kk = 0; kk < 4; ++kk) {
;         const bf16x8 pa = packp(kk < 2 ? X0 : X1, (kk & 1) * 8);
; #pragma unroll
;         for (int eb = 0; eb < NEB; ++eb) {
;             const s16x4 lo = vtr(vlane + (kk * 16) * VRS + eb * 64), hi = vtr(vlane + (kk * 16 + 8) * VRS + eb * 64);
;             OT[eb] = __builtin_amdgcn_mfma_f32_32x32x16_bf16(cat8(lo, hi), pa, OT[eb], 0, 0, 0);
;         }
;         if (SB) __builtin_amdgcn_sched_barrier(0);
;     }
; }
.Lpf1_nores:
	v_sub_f32_e32 v164, v175, v163
	v_pk_add_f32 v[66:67], v[66:67], v[164:165] op_sel_hi:[1,0]
	v_pk_add_f32 v[68:69], v[68:69], v[164:165] op_sel_hi:[1,0]
	v_pk_add_f32 v[70:71], v[70:71], v[164:165] op_sel_hi:[1,0]
	v_pk_add_f32 v[72:73], v[72:73], v[164:165] op_sel_hi:[1,0]
	v_pk_add_f32 v[74:75], v[74:75], v[164:165] op_sel_hi:[1,0]
	v_pk_add_f32 v[76:77], v[76:77], v[164:165] op_sel_hi:[1,0]
	v_pk_add_f32 v[78:79], v[78:79], v[164:165] op_sel_hi:[1,0]
	v_pk_add_f32 v[80:81], v[80:81], v[164:165] op_sel_hi:[1,0]
	v_exp_f32_e32 v66, v66
	v_exp_f32_e32 v67, v67
	v_exp_f32_e32 v68, v68
	v_exp_f32_e32 v69, v69
	v_exp_f32_e32 v70, v70
	v_exp_f32_e32 v71, v71
	v_exp_f32_e32 v72, v72
	v_exp_f32_e32 v73, v73
	v_exp_f32_e32 v74, v74
	v_exp_f32_e32 v75, v75
	v_exp_f32_e32 v76, v76
	v_exp_f32_e32 v77, v77
	v_exp_f32_e32 v78, v78
	v_exp_f32_e32 v79, v79
	v_exp_f32_e32 v80, v80
	v_exp_f32_e32 v81, v81
	v_pk_add_f32 v[188:189], v[66:67], v[68:69]
	v_pk_add_f32 v[190:191], v[70:71], v[72:73]
	v_pk_add_f32 v[188:189], v[188:189], v[74:75]
	v_pk_add_f32 v[190:191], v[190:191], v[76:77]
	v_pk_add_f32 v[188:189], v[188:189], v[78:79]
	v_pk_add_f32 v[190:191], v[190:191], v[80:81]
	v_cvt_pk_bf16_f32 v66, v66, v67
	v_cvt_pk_bf16_f32 v67, v68, v69
	v_cvt_pk_bf16_f32 v68, v70, v71
	v_cvt_pk_bf16_f32 v69, v72, v73
	v_cvt_pk_bf16_f32 v70, v74, v75
	v_cvt_pk_bf16_f32 v71, v76, v77
	v_cvt_pk_bf16_f32 v72, v78, v79
	v_cvt_pk_bf16_f32 v73, v80, v81
	ds_read_b64_tr_b16 v[74:75], v156 offset:62464
	ds_read_b64_tr_b16 v[76:77], v156 offset:65024
	ds_read_b64_tr_b16 v[78:79], v156 offset:62528
	ds_read_b64_tr_b16 v[80:81], v156 offset:65088
	ds_read_b64_tr_b16 v[244:245], v156 offset:62592
	ds_read_b64_tr_b16 v[246:247], v156 offset:65152
	ds_read_b64_tr_b16 v[248:249], v156 offset:62656
	ds_read_b64_tr_b16 v[250:251], v156 offset:65216
	s_waitcnt lgkmcnt(8)
	v_mfma_f32_32x32x16_bf16 v[50:65], v[166:169], v[66:69], v[50:65]
	v_mfma_f32_32x32x16_bf16 v[34:49], v[176:179], v[66:69], v[34:49]
	v_mfma_f32_32x32x16_bf16 v[18:33], v[180:183], v[66:69], v[18:33]
	v_mfma_f32_32x32x16_bf16 v[2:17], v[184:187], v[66:69], v[2:17]
	ds_read_b64_tr_b16 v[166:167], v157 offset:10240
	ds_read_b64_tr_b16 v[168:169], v157 offset:12800
	ds_read_b64_tr_b16 v[176:177], v157 offset:10304
	ds_read_b64_tr_b16 v[178:179], v157 offset:12864
	ds_read_b64_tr_b16 v[180:181], v157 offset:10368
	ds_read_b64_tr_b16 v[182:183], v157 offset:12928
	ds_read_b64_tr_b16 v[184:185], v157 offset:10432
	ds_read_b64_tr_b16 v[186:187], v157 offset:12992
	s_waitcnt lgkmcnt(8)
	v_mfma_f32_32x32x16_bf16 v[50:65], v[74:77], v[70:73], v[50:65]
	v_mfma_f32_32x32x16_bf16 v[34:49], v[78:81], v[70:73], v[34:49]
	v_mfma_f32_32x32x16_bf16 v[18:33], v[244:247], v[70:73], v[18:33]
	v_mfma_f32_32x32x16_bf16 v[2:17], v[248:251], v[70:73], v[2:17]
	ds_read_b64_tr_b16 v[74:75], v157 offset:15360
	ds_read_b64_tr_b16 v[76:77], v157 offset:17920
	ds_read_b64_tr_b16 v[78:79], v157 offset:15424
	ds_read_b64_tr_b16 v[80:81], v157 offset:17984
	ds_read_b64_tr_b16 v[244:245], v157 offset:15488
	ds_read_b64_tr_b16 v[246:247], v157 offset:18048
	ds_read_b64_tr_b16 v[248:249], v157 offset:15552
	ds_read_b64_tr_b16 v[250:251], v157 offset:18112
	v_pk_add_f32 v[82:83], v[82:83], v[164:165] op_sel_hi:[1,0]
	v_pk_add_f32 v[84:85], v[84:85], v[164:165] op_sel_hi:[1,0]
	v_pk_add_f32 v[86:87], v[86:87], v[164:165] op_sel_hi:[1,0]
	v_pk_add_f32 v[88:89], v[88:89], v[164:165] op_sel_hi:[1,0]
	v_pk_add_f32 v[90:91], v[90:91], v[164:165] op_sel_hi:[1,0]
	v_pk_add_f32 v[92:93], v[92:93], v[164:165] op_sel_hi:[1,0]
	v_pk_add_f32 v[94:95], v[94:95], v[164:165] op_sel_hi:[1,0]
	v_pk_add_f32 v[96:97], v[96:97], v[164:165] op_sel_hi:[1,0]
	v_exp_f32_e32 v82, v82
	v_exp_f32_e32 v83, v83
	v_exp_f32_e32 v84, v84
	v_exp_f32_e32 v85, v85
	v_exp_f32_e32 v86, v86
	v_exp_f32_e32 v87, v87
	v_exp_f32_e32 v88, v88
	v_exp_f32_e32 v89, v89
	v_exp_f32_e32 v90, v90
	v_exp_f32_e32 v91, v91
	v_exp_f32_e32 v92, v92
	v_exp_f32_e32 v93, v93
	v_exp_f32_e32 v94, v94
	v_exp_f32_e32 v95, v95
	v_exp_f32_e32 v96, v96
	v_exp_f32_e32 v97, v97
	v_pk_add_f32 v[188:189], v[188:189], v[82:83]
	v_pk_add_f32 v[190:191], v[190:191], v[84:85]
	v_pk_add_f32 v[188:189], v[188:189], v[86:87]
	v_pk_add_f32 v[190:191], v[190:191], v[88:89]
	v_pk_add_f32 v[188:189], v[188:189], v[90:91]
	v_pk_add_f32 v[190:191], v[190:191], v[92:93]
	v_pk_add_f32 v[188:189], v[188:189], v[94:95]
	v_pk_add_f32 v[190:191], v[190:191], v[96:97]
	v_cvt_pk_bf16_f32 v82, v82, v83
	v_cvt_pk_bf16_f32 v83, v84, v85
	v_cvt_pk_bf16_f32 v84, v86, v87
	v_cvt_pk_bf16_f32 v85, v88, v89
	v_cvt_pk_bf16_f32 v86, v90, v91
	v_cvt_pk_bf16_f32 v87, v92, v93
	v_cvt_pk_bf16_f32 v88, v94, v95
	v_cvt_pk_bf16_f32 v89, v96, v97
	v_pk_add_f32 v[188:189], v[188:189], v[190:191]
	s_waitcnt lgkmcnt(8)
	v_mfma_f32_32x32x16_bf16 v[50:65], v[166:169], v[82:85], v[50:65]
	v_mfma_f32_32x32x16_bf16 v[34:49], v[176:179], v[82:85], v[34:49]
	v_mfma_f32_32x32x16_bf16 v[18:33], v[180:183], v[82:85], v[18:33]
	v_mfma_f32_32x32x16_bf16 v[2:17], v[184:187], v[82:85], v[2:17]
	v_add_f32_e32 v0, v188, v189
	v_add_f32_e32 v159, v159, v0
	s_waitcnt lgkmcnt(0)
	v_mfma_f32_32x32x16_bf16 v[50:65], v[74:77], v[86:89], v[50:65]
	v_mfma_f32_32x32x16_bf16 v[34:49], v[78:81], v[86:89], v[34:49]
	v_mfma_f32_32x32x16_bf16 v[18:33], v[244:247], v[86:89], v[18:33]
	v_mfma_f32_32x32x16_bf16 v[2:17], v[248:251], v[86:89], v[2:17]
	s_branch .Lpf1_end
